# attention K/V tile loads: per-thread pieces qt+4i so four lanes of a key row read 64 contiguous bytes per instruction (LDS image unchanged)
# speedup vs baseline: 1.0151x; 1.0035x over previous
; #define LAS __attribute__((address_space(3)))
; #define AT_LOAD(t_) do { const int ks0_ = 128 * (qb - 1) + 64 * (t_); if (ks0_ >= 0) { const size_t ktok_ = rowb + (size_t)(ks0_ + kr) * dil + r; const bf16* kp_ = P + pidx(ktok_, 1536 + head * 128 + qt * 32); \
;         _Pragma("unroll") for (int i = 0; i < 4; ++i) { kreg[i] = *(const v4u*)(kp_ + 8 * i); vreg[i] = *(const v4u*)(kp_ + (size_t)6 * TH * 256 + 8 * i); } } } while (0)
; DI void attn_unit(LAS unsigned char* lds, const bf16* P, bf16* OG, float* LSE, const float* relb, int u) {
;     ...
;     const int bp = u & 7, t2 = u >> 3, head = t2 % 12, bl = t2 / 12, g = head >> 2, hs = head & 3;
;     const int dil = (g == 0) ? 1 : ((g == 1) ? 4 : 16), nbs = (g == 0) ? 4 : ((g == 1) ? 2 : 0);
;     const int blk = 2 * bp + hw, r = blk >> nbs, qb = blk & ((1 << nbs) - 1);
;     const size_t rowb = (size_t)bl * 2048;
;     LAS unsigned char* Kl = lds + hw * A_HALF + A_K; LAS unsigned char* Vl = lds + hw * A_HALF + A_V; LAS float* biasT = (LAS float*)(lds + hw * A_HALF + A_BIAS);
;     const LAS float* gq = (const LAS float*)(lds + A_GQ);
; #pragma unroll
;     for (int jj = 0; jj < 2; ++jj) { const int j = htid + 256 * jj;
;         if (j < 320) { const int delta = j - 96; float val = -1e30f;
;             if (delta >= 0 && delta <= 128) { const int dist = delta * dil; int bucket;
;                 if (dist < 16) bucket = dist; else { const float d = (float)dist; int lg = 16 + (int)(logf(d / 16.0f) / logf(128.0f) * 16.0f); bucket = lg < 31 ? lg : 31; }
;                 val = relb[bucket * 12 + head] * 1.4426950408889634f; }
;             biasT[j] = val; } }
;     const int kr = htid >> 2, qt = htid & 3;
;     v4u kreg[4], vreg[4];
;     ...
;     const int tstart = (g == 2) ? 2 : 0;
;     AT_LOAD(tstart);
.LBB0_415:
	s_or_b64 exec, exec, s[10:11]
	s_ashr_i32 s5, s24, 8
	s_mul_i32 s25, s5, 0x9900
	s_add_i32 s26, s25, 0
	v_lshl_add_u32 v2, v4, 2, s26
	v_mov_b32_e32 v217, v2
	v_or_b32_e32 v0, 0x100, v4
	s_movk_i32 s7, 0x140
	v_cmp_gt_u32_e32 vcc, s7, v0
	s_and_saveexec_b64 s[10:11], vcc
	ds_write_b32 v2, v193 offset:38912
	s_or_b64 exec, exec, s[10:11]
	s_and_b64 s[10:11], s[16:17], exec
	s_cselect_b32 s7, 2, 0
	s_and_b64 s[10:11], s[14:15], exec
	s_cselect_b32 s7, 4, s7
	s_lshl_b32 s9, s18, 1
	s_and_b32 s9, s9, 14
	s_add_i32 s5, s5, s9
	s_lshl_b32 s10, -1, s7
	s_ashr_i32 s9, s8, 31
	s_ashr_i32 s28, s5, s7
	s_andn2_b32 s5, s5, s10
	s_lshl_b64 s[18:19], s[8:9], 11
	s_cmp_eq_u32 s6, 2
	s_cselect_b32 s27, 2, 0
	s_lshl_b32 s7, s5, 7
	s_lshl_b32 s23, s27, 6
	s_add_i32 s29, s7, s23
	s_addk_i32 s29, 0xff80
	s_cmp_gt_i32 s29, -1
	v_and_b32_e32 v9, 3, v8
	s_cbranch_scc1 .LBB0_419
	s_and_b64 s[8:9], s[16:17], exec
	s_cselect_b32 s5, 2, 4
	s_and_b64 s[8:9], s[14:15], exec
	s_cselect_b32 s8, 0, s5
	s_ashr_i32 s5, s28, 31
	s_add_u32 s10, s18, s28
	s_addc_u32 s11, s19, s5
	s_lshl_b32 s5, s4, 7
	v_readlane_b32 s20, v254, 6
	s_add_i32 s12, s5, 0x600
	v_readlane_b32 s21, v254, 7
	s_and_b32 s9, s5, 0x80
	s_mov_b32 s35, s21
	s_lshr_b32 s34, s12, 8
	s_lshl_b64 s[12:13], s[34:35], 24
	s_mov_b32 s34, s9
	v_lshl_or_b32 v0, v9, 3, s9
	v_writelane_b32 v254, s34, 6
	s_mov_b64 s[20:21], 0
	v_mov_b64_e32 v[2:3], v[0:1]
	v_writelane_b32 v254, s35, 7
	s_andn2_b64 vcc, exec, s[20:21]
	v_lshrrev_b32_e32 v10, 2, v4
	s_cbranch_vccnz .LBB0_421
	s_branch .LBB0_420

; DI size_t pidx(size_t row, int col) { return (size_t)(col >> 8) * ((size_t)TH * 256) + row * 256 + (size_t)(col & 255); }
; DI float lo_f(unsigned u) { return __uint_as_float(u << 16); }
; DI float hi_f(unsigned u) { return __uint_as_float(u & 0xffff0000u); }
; #define AT_LOAD(t_) do { const int ks0_ = 128 * (qb - 1) + 64 * (t_); if (ks0_ >= 0) { const size_t ktok_ = rowb + (size_t)(ks0_ + kr) * dil + r; const bf16* kp_ = P + pidx(ktok_, 1536 + head * 128 + qt * 32); \
;         _Pragma("unroll") for (int i = 0; i < 4; ++i) { kreg[i] = *(const v4u*)(kp_ + 8 * i); vreg[i] = *(const v4u*)(kp_ + (size_t)6 * TH * 256 + 8 * i); } } } while (0)
; DI void attn_unit(LAS unsigned char* lds, const bf16* P, bf16* OG, float* LSE, const float* relb, int u) {
;     ...
;     const int tstart = (g == 2) ? 2 : 0;
;     AT_LOAD(tstart);
;     const int qmin = 128 * qb + 32 * w, qsub = qmin + r32; const size_t qtok = rowb + (size_t)qsub * dil + r;
;     bf16x8 qf[8];
;     { const bf16* qrow = P + pidx(qtok, head * 128); v4u qraw[8]; float ss = 0.f;
; #pragma unroll
;         for (int kk = 0; kk < 8; ++kk) { qraw[kk] = *(const v4u*)(qrow + 16 * kk + 8 * hh); const v4u q = qraw[kk];
;             ss += lo_f(q.x) * lo_f(q.x) + hi_f(q.x) * hi_f(q.x) + lo_f(q.y) * lo_f(q.y) + hi_f(q.y) * hi_f(q.y) + lo_f(q.z) * lo_f(q.z) + hi_f(q.z) * hi_f(q.z) + lo_f(q.w) * lo_f(q.w) + hi_f(q.w) * hi_f(q.w); }
;         ss += __shfl_xor(ss, 32);
;         const float rs = rsqrtf(ss * (1.0f / 128.0f) + 1e-6f) * (0.08838834764831845f * 1.4426950408889634f);
.LBB0_420:
	s_and_b64 s[8:9], s[16:17], exec
	s_cselect_b32 s5, 2, 4
	s_and_b64 s[8:9], s[14:15], exec
	s_cselect_b32 s8, 0, s5
	s_ashr_i32 s5, s28, 31
	s_add_u32 s10, s18, s28
	s_addc_u32 s11, s19, s5
	s_lshl_b32 s5, s4, 7
	v_readlane_b32 s12, v254, 6
	s_add_i32 s9, s5, 0x600
	v_readlane_b32 s13, v254, 7
	v_or_b32_e32 v0, s29, v10
	s_mov_b32 s17, s13
	s_lshr_b32 s16, s9, 8
	v_lshlrev_b64 v[2:3], s8, v[0:1]
	s_and_b32 s9, s5, 0x80
	s_lshl_b64 s[12:13], s[16:17], 24
	v_lshl_add_u64 v[2:3], v[2:3], 0, s[10:11]
	s_add_u32 s14, s86, s12
	v_lshl_or_b32 v0, v9, 3, s9
	s_addc_u32 s15, s87, s13
	v_lshlrev_b64 v[2:3], 9, v[2:3]
	v_lshl_add_u64 v[2:3], s[14:15], 0, v[2:3]
	v_lshlrev_b32_e32 v4, 1, v0
	v_mov_b32_e32 v5, v1
	v_lshl_add_u64 v[2:3], v[2:3], 0, v[4:5]
	s_mov_b64 s[14:15], 0x6000000
	v_lshl_add_u64 v[4:5], v[2:3], 0, s[14:15]
	s_mov_b32 s14, 0x6000000
	global_load_dwordx4 v[98:101], v[2:3], off offset:192
	global_load_dwordx4 v[102:105], v[2:3], off offset:128
	global_load_dwordx4 v[106:109], v[2:3], off offset:64
	global_load_dwordx4 v[110:113], v[2:3], off
	v_add_co_u32_e32 v2, vcc, s14, v2
	s_mov_b32 s16, s9
	s_nop 0
	v_addc_co_u32_e32 v3, vcc, 0, v3, vcc
	global_load_dwordx4 v[114:117], v[2:3], off
	global_load_dwordx4 v[118:121], v[4:5], off offset:192
	global_load_dwordx4 v[122:125], v[4:5], off offset:128
	global_load_dwordx4 v[126:129], v[4:5], off offset:64
	v_writelane_b32 v254, s16, 6
	v_mov_b64_e32 v[2:3], v[0:1]
	s_nop 0
	v_writelane_b32 v254, s17, 7
.LBB0_421:
	s_lshr_b32 s9, s24, 1
	s_and_b32 s14, s9, 0x60
	v_and_b32_e32 v11, 31, v8
	s_or_b32 s9, s7, s14
	s_ashr_i32 s16, s4, 1
	v_or_b32_e32 v0, s9, v11
	s_ashr_i32 s17, s16, 31
	v_lshlrev_b64 v[4:5], s8, v[0:1]
	s_lshl_b64 s[16:17], s[16:17], 24
	v_lshl_add_u64 v[178:179], v[4:5], 0, s[10:11]
	s_add_u32 s16, s86, s16
	s_addc_u32 s17, s87, s17
	v_lshlrev_b64 v[4:5], 9, v[178:179]
	v_lshl_add_u64 v[4:5], s[16:17], 0, v[4:5]
	v_readlane_b32 s16, v254, 6
	v_bfe_u32 v183, v8, 5, 1
	v_readlane_b32 s17, v254, 7
	v_lshlrev_b32_e32 v0, 4, v183
	s_mov_b32 s15, 0x800000
	v_lshl_add_u64 v[4:5], s[16:17], 1, v[4:5]
	v_lshl_add_u64 v[36:37], v[4:5], 0, v[0:1]
	global_load_dwordx4 v[4:7], v[36:37], off offset:32
	global_load_dwordx4 v[12:15], v[36:37], off
	global_load_dwordx4 v[16:19], v[36:37], off offset:96
	global_load_dwordx4 v[20:23], v[36:37], off offset:64
	global_load_dwordx4 v[24:27], v[36:37], off offset:160
	global_load_dwordx4 v[28:31], v[36:37], off offset:128
	global_load_dwordx4 v[32:35], v[36:37], off offset:224
	s_nop 0
	global_load_dwordx4 v[36:39], v[36:37], off offset:192
	s_add_u32 s12, s86, s12
	s_addc_u32 s13, s87, s13
	v_lshl_add_u64 v[180:181], v[2:3], 1, s[12:13]
	v_lshlrev_b32_e32 v2, 2, v8
	v_lshlrev_b32_e32 v185, 2, v183
	s_lshl_b32 s13, s24, 1
	s_and_b32 s13, s13, 0x180
	s_add_i32 s25, s25, s13
	s_movk_i32 s16, 0x110
	s_lshl_b32 s13, s27, 8
	v_mov_b32_e32 v3, v1
	s_add_i32 s12, s27, -1
	v_mov_b32_e32 v206, 0xf149f2ca
	v_mov_b32_e32 v205, 0
	s_waitcnt vmcnt(7)
	v_and_b32_e32 v43, 0xffff0000, v4
	s_waitcnt vmcnt(6)
	v_and_b32_e32 v42, 0xffff0000, v12
	v_lshlrev_b32_e32 v41, 16, v4
	v_lshlrev_b32_e32 v40, 16, v12
	v_lshlrev_b32_e32 v49, 16, v6
	v_and_b32_e32 v51, 0xffff0000, v6
	v_lshlrev_b32_e32 v53, 16, v7
	v_and_b32_e32 v55, 0xffff0000, v7
	v_pk_mul_f32 v[6:7], v[42:43], v[42:43]
	v_lshlrev_b32_e32 v45, 16, v5
	v_lshlrev_b32_e32 v44, 16, v13
	v_pk_fma_f32 v[6:7], v[40:41], v[40:41], v[6:7]
	v_and_b32_e32 v47, 0xffff0000, v5
	v_and_b32_e32 v46, 0xffff0000, v13
	s_waitcnt vmcnt(5)
	v_and_b32_e32 v59, 0xffff0000, v16
	s_waitcnt vmcnt(4)
	v_and_b32_e32 v58, 0xffff0000, v20
	v_pk_fma_f32 v[6:7], v[44:45], v[44:45], v[6:7]
	v_lshlrev_b32_e32 v48, 16, v14
	v_lshlrev_b32_e32 v57, 16, v16
	v_lshlrev_b32_e32 v56, 16, v20
	v_pk_mul_f32 v[12:13], v[58:59], v[58:59]
	v_pk_fma_f32 v[6:7], v[46:47], v[46:47], v[6:7]
	v_and_b32_e32 v50, 0xffff0000, v14
	v_lshlrev_b32_e32 v61, 16, v17
	v_lshlrev_b32_e32 v60, 16, v21
	s_waitcnt vmcnt(3)
	v_and_b32_e32 v71, 0xffff0000, v24
	s_waitcnt vmcnt(2)
	v_and_b32_e32 v70, 0xffff0000, v28
	v_pk_fma_f32 v[12:13], v[56:57], v[56:57], v[12:13]
	v_pk_fma_f32 v[6:7], v[48:49], v[48:49], v[6:7]
	v_lshlrev_b32_e32 v52, 16, v15
	v_and_b32_e32 v54, 0xffff0000, v15
	v_and_b32_e32 v63, 0xffff0000, v17
	v_and_b32_e32 v62, 0xffff0000, v21
	v_lshlrev_b32_e32 v20, 16, v22
	v_and_b32_e32 v64, 0xffff0000, v22
	v_lshlrev_b32_e32 v66, 16, v23
	v_and_b32_e32 v68, 0xffff0000, v23
	v_lshlrev_b32_e32 v23, 16, v24
	v_lshlrev_b32_e32 v22, 16, v28
	v_pk_mul_f32 v[14:15], v[70:71], v[70:71]
	v_pk_fma_f32 v[12:13], v[60:61], v[60:61], v[12:13]
	v_pk_fma_f32 v[6:7], v[50:51], v[50:51], v[6:7]
	v_lshlrev_b32_e32 v21, 16, v18
	v_lshlrev_b32_e32 v73, 16, v25
	v_lshlrev_b32_e32 v72, 16, v29
	v_pk_fma_f32 v[14:15], v[22:23], v[22:23], v[14:15]
	v_pk_fma_f32 v[12:13], v[62:63], v[62:63], v[12:13]
	v_pk_fma_f32 v[6:7], v[52:53], v[52:53], v[6:7]
	v_and_b32_e32 v65, 0xffff0000, v18
	v_and_b32_e32 v25, 0xffff0000, v25
	v_and_b32_e32 v24, 0xffff0000, v29
	v_pk_fma_f32 v[14:15], v[72:73], v[72:73], v[14:15]
	v_pk_fma_f32 v[12:13], v[20:21], v[20:21], v[12:13]
	v_pk_fma_f32 v[16:17], v[54:55], v[54:55], v[6:7]
	s_waitcnt vmcnt(1)
	v_and_b32_e32 v7, 0xffff0000, v32
	s_waitcnt vmcnt(0)
; #define LAS __attribute__((address_space(3)))
; DI size_t pidx(size_t row, int col) { return (size_t)(col >> 8) * ((size_t)TH * 256) + row * 256 + (size_t)(col & 255); }
; DI float lo_f(unsigned u) { return __uint_as_float(u << 16); }
; DI float hi_f(unsigned u) { return __uint_as_float(u & 0xffff0000u); }
; DI void attn_unit(LAS unsigned char* lds, const bf16* P, bf16* OG, float* LSE, const float* relb, int u) {
;     ...
;     { const bf16* qrow = P + pidx(qtok, head * 128); v4u qraw[8]; float ss = 0.f;
; #pragma unroll
;         for (int kk = 0; kk < 8; ++kk) { qraw[kk] = *(const v4u*)(qrow + 16 * kk + 8 * hh); const v4u q = qraw[kk];
;             ss += lo_f(q.x) * lo_f(q.x) + hi_f(q.x) * hi_f(q.x) + lo_f(q.y) * lo_f(q.y) + hi_f(q.y) * hi_f(q.y) + lo_f(q.z) * lo_f(q.z) + hi_f(q.z) * hi_f(q.z) + lo_f(q.w) * lo_f(q.w) + hi_f(q.w) * hi_f(q.w); }
;         ss += __shfl_xor(ss, 32);
;         const float rs = rsqrtf(ss * (1.0f / 128.0f) + 1e-6f) * (0.08838834764831845f * 1.4426950408889634f);
; #pragma unroll
;         for (int kk = 0; kk < 8; ++kk) { const v4u q = qraw[kk]; const f32x4 g0 = *(const LAS f32x4*)(gq + 16 * kk + 8 * hh), g1 = *(const LAS f32x4*)(gq + 16 * kk + 8 * hh + 4);
;             qf[kk] = pack8(lo_f(q.x) * rs * g0[0], hi_f(q.x) * rs * g0[1], lo_f(q.y) * rs * g0[2], hi_f(q.y) * rs * g0[3], lo_f(q.z) * rs * g1[0], hi_f(q.z) * rs * g1[1], lo_f(q.w) * rs * g1[2], hi_f(q.w) * rs * g1[3]); }
	v_mov_b32_e32 v218, 0xf149f2ca
	v_mul_f32_e32 v216, 0x3fb8aa3b, v216
	v_cndmask_b32_e64 v218, v218, v216, s[98:99]
	ds_write_b32 v217, v218 offset:37888
	s_mov_b64 s[100:101], exec
	s_and_b64 exec, exec, s[0:1]
	v_mov_b32_e32 v182, v219
	s_mov_b64 exec, s[100:101]
	v_and_b32_e32 v6, 0xffff0000, v36
	v_lshlrev_b32_e32 v67, 16, v19
	v_and_b32_e32 v69, 0xffff0000, v19
	v_lshlrev_b32_e32 v29, 16, v26
	v_lshlrev_b32_e32 v28, 16, v30
	v_lshlrev_b32_e32 v5, 16, v32
	v_pk_fma_f32 v[14:15], v[24:25], v[24:25], v[14:15]
	v_pk_fma_f32 v[12:13], v[64:65], v[64:65], v[12:13]
	v_lshlrev_b32_e32 v4, 16, v36
	v_pk_mul_f32 v[18:19], v[6:7], v[6:7]
	v_and_b32_e32 v75, 0xffff0000, v26
	v_and_b32_e32 v74, 0xffff0000, v30
	v_lshlrev_b32_e32 v76, 16, v31
	v_and_b32_e32 v26, 0xffff0000, v31
	v_pk_fma_f32 v[14:15], v[28:29], v[28:29], v[14:15]
	v_pk_fma_f32 v[12:13], v[66:67], v[66:67], v[12:13]
	v_pk_fma_f32 v[18:19], v[4:5], v[4:5], v[18:19]
	v_lshlrev_b32_e32 v31, 16, v33
	v_lshlrev_b32_e32 v30, 16, v37
	v_lshlrev_b32_e32 v77, 16, v27
	v_pk_fma_f32 v[14:15], v[74:75], v[74:75], v[14:15]
	v_pk_fma_f32 v[12:13], v[68:69], v[68:69], v[12:13]
	v_pk_fma_f32 v[18:19], v[30:31], v[30:31], v[18:19]
	v_and_b32_e32 v33, 0xffff0000, v33
	v_and_b32_e32 v32, 0xffff0000, v37
	v_add_f32_e32 v16, v16, v17
	v_and_b32_e32 v27, 0xffff0000, v27
	v_pk_fma_f32 v[14:15], v[76:77], v[76:77], v[14:15]
	v_pk_fma_f32 v[18:19], v[32:33], v[32:33], v[18:19]
	v_lshlrev_b32_e32 v37, 16, v34
	v_lshlrev_b32_e32 v36, 16, v38
	v_add_f32_e32 v12, v16, v12
	v_pk_fma_f32 v[14:15], v[26:27], v[26:27], v[14:15]
	v_pk_fma_f32 v[18:19], v[36:37], v[36:37], v[18:19]
	v_and_b32_e32 v79, 0xffff0000, v34
	v_and_b32_e32 v78, 0xffff0000, v38
	v_add_f32_e32 v12, v12, v13
	v_pk_fma_f32 v[18:19], v[78:79], v[78:79], v[18:19]
	v_lshlrev_b32_e32 v81, 16, v35
	v_lshlrev_b32_e32 v80, 16, v39
	v_add_f32_e32 v12, v12, v14
	v_and_b32_e32 v14, 64, v194
	v_pk_fma_f32 v[18:19], v[80:81], v[80:81], v[18:19]
	v_and_b32_e32 v35, 0xffff0000, v35
	v_and_b32_e32 v34, 0xffff0000, v39
	v_xor_b32_e32 v13, 32, v194
	v_add_u32_e32 v38, 64, v14
	v_pk_fma_f32 v[18:19], v[34:35], v[34:35], v[18:19]
	v_add_f32_e32 v12, v12, v15
	v_cmp_lt_i32_e32 vcc, v13, v38
	v_add_f32_e32 v12, v12, v18
	v_add_f32_e32 v12, v12, v19
	v_cndmask_b32_e32 v13, v194, v13, vcc
	v_lshlrev_b32_e32 v184, 2, v13
	ds_bpermute_b32 v13, v184, v12
	s_waitcnt lgkmcnt(0)
	v_add_f32_e32 v12, v12, v13
	v_fmamk_f32 v12, v12, 0x3c000000, v192
	v_mul_f32_e32 v13, 0x4b800000, v12
	v_cmp_gt_f32_e32 vcc, s15, v12
	s_movk_i32 s15, 0x140
	s_nop 0
	v_cndmask_b32_e32 v12, v12, v13, vcc
	v_rsq_f32_e32 v16, v12
	v_lshl_add_u32 v12, v183, 5, 0
	v_add_u32_e32 v39, 0x13200, v12
	ds_read_b128 v[12:15], v39
	v_mul_f32_e32 v17, 0x45800000, v16
	v_cndmask_b32_e32 v16, v16, v17, vcc
	v_mul_f32_e32 v82, 0x3e0293ee, v16
	ds_read_b128 v[16:19], v39 offset:16
	v_mul_f32_e32 v40, v82, v40
	s_waitcnt lgkmcnt(1)
	v_mul_f32_e32 v12, v12, v40
	v_mul_f32_e32 v40, v82, v42
	v_mul_f32_e32 v13, v13, v40
	v_mul_f32_e32 v40, v82, v44
	v_mul_f32_e32 v14, v14, v40
	v_mul_f32_e32 v40, v82, v46
	v_mul_f32_e32 v15, v15, v40
	v_mul_f32_e32 v40, v82, v48
	s_waitcnt lgkmcnt(0)
	v_mul_f32_e32 v16, v16, v40
	v_mul_f32_e32 v40, v82, v50
	v_mul_f32_e32 v17, v17, v40
	v_mul_f32_e32 v40, v82, v52
	v_mul_f32_e32 v18, v18, v40
	v_mul_f32_e32 v40, v82, v54
	v_mul_f32_e32 v19, v19, v40
	v_cvt_pk_bf16_f32 v130, v12, v13
	v_cvt_pk_bf16_f32 v131, v14, v15
	v_cvt_pk_bf16_f32 v132, v16, v17
	v_cvt_pk_bf16_f32 v133, v18, v19
	ds_read_b128 v[12:15], v39 offset:64
	ds_read_b128 v[16:19], v39 offset:80
	v_mul_f32_e32 v40, v82, v41
	v_mul_f32_e32 v20, v82, v20
	v_mul_f32_e32 v4, v82, v4
	s_waitcnt lgkmcnt(1)
	v_mul_f32_e32 v12, v12, v40
	v_mul_f32_e32 v40, v82, v43
	v_mul_f32_e32 v13, v13, v40
	v_mul_f32_e32 v40, v82, v45
	v_mul_f32_e32 v14, v14, v40
	v_mul_f32_e32 v40, v82, v47
	v_mul_f32_e32 v15, v15, v40
	v_mul_f32_e32 v40, v82, v49
	s_waitcnt lgkmcnt(0)
	v_mul_f32_e32 v16, v16, v40
	v_mul_f32_e32 v40, v82, v51
	v_mul_f32_e32 v17, v17, v40
	v_mul_f32_e32 v40, v82, v53
	v_mul_f32_e32 v18, v18, v40
	v_mul_f32_e32 v40, v82, v55
	v_mul_f32_e32 v19, v19, v40
	v_cvt_pk_bf16_f32 v134, v12, v13
	v_cvt_pk_bf16_f32 v135, v14, v15
	v_cvt_pk_bf16_f32 v136, v16, v17
	v_cvt_pk_bf16_f32 v137, v18, v19
	ds_read_b128 v[12:15], v39 offset:128
	ds_read_b128 v[16:19], v39 offset:144
	v_mul_f32_e32 v40, v82, v56
	v_mul_f32_e32 v6, v82, v6
	v_mul_f32_e32 v5, v82, v5
	s_waitcnt lgkmcnt(1)
	v_mul_f32_e32 v12, v12, v40
	v_mul_f32_e32 v40, v82, v58
	s_waitcnt lgkmcnt(0)
	v_mul_f32_e32 v16, v16, v20
	v_mul_f32_e32 v20, v82, v64
	v_mul_f32_e32 v13, v13, v40
	v_mul_f32_e32 v40, v82, v60
	v_mul_f32_e32 v17, v17, v20
	v_mul_f32_e32 v20, v82, v66
	v_mul_f32_e32 v14, v14, v40
	v_mul_f32_e32 v40, v82, v62
	v_mul_f32_e32 v18, v18, v20
	v_mul_f32_e32 v20, v82, v68
	v_mul_f32_e32 v15, v15, v40
	v_mul_f32_e32 v19, v19, v20
	v_cvt_pk_bf16_f32 v138, v12, v13
	v_cvt_pk_bf16_f32 v139, v14, v15
	v_cvt_pk_bf16_f32 v140, v16, v17
	v_cvt_pk_bf16_f32 v141, v18, v19
	ds_read_b128 v[12:15], v39 offset:192
	ds_read_b128 v[16:19], v39 offset:208
	v_mul_f32_e32 v20, v82, v57
	v_mul_f32_e32 v7, v82, v7
	s_waitcnt lgkmcnt(1)
	v_mul_f32_e32 v12, v20, v12
	v_mul_f32_e32 v20, v82, v59
	v_mul_f32_e32 v13, v20, v13
	v_mul_f32_e32 v20, v82, v61
	v_mul_f32_e32 v14, v20, v14
	v_mul_f32_e32 v20, v82, v63
	v_mul_f32_e32 v15, v20, v15
	v_mul_f32_e32 v20, v82, v21
	s_waitcnt lgkmcnt(0)
; #define LAS __attribute__((address_space(3)))
; DI float lo_f(unsigned u) { return __uint_as_float(u << 16); }
; DI float hi_f(unsigned u) { return __uint_as_float(u & 0xffff0000u); }
; DI unsigned pk2(float lo, float hi) { return pg8::cvt_pk_bf16(lo, hi); }
; DI void attn_unit(LAS unsigned char* lds, const bf16* P, bf16* OG, float* LSE, const float* relb, int u) {
;     ...
; #pragma unroll
;         for (int kk = 0; kk < 8; ++kk) { const v4u q = qraw[kk]; const f32x4 g0 = *(const LAS f32x4*)(gq + 16 * kk + 8 * hh), g1 = *(const LAS f32x4*)(gq + 16 * kk + 8 * hh + 4);
;             qf[kk] = pack8(lo_f(q.x) * rs * g0[0], hi_f(q.x) * rs * g0[1], lo_f(q.y) * rs * g0[2], hi_f(q.y) * rs * g0[3], lo_f(q.z) * rs * g1[0], hi_f(q.z) * rs * g1[1], lo_f(q.w) * rs * g1[2], hi_f(q.w) * rs * g1[3]); }
;     }
;     f32x16 O[4];
; #pragma unroll
;     for (int dt = 0; dt < 4; ++dt)
; #pragma unroll
;         for (int i = 0; i < 16; ++i) O[dt][i] = 0.f;
;     float m = -1e30f, l = 0.f;
;     ...
;             for (int i = 0; i < 4; ++i) { const v4u q = kreg[i];
;                 v4u o; o.x = pk2(lo_f(q.x) * rs, hi_f(q.x) * rs); o.y = pk2(lo_f(q.y) * rs, hi_f(q.y) * rs); o.z = pk2(lo_f(q.z) * rs, hi_f(q.z) * rs); o.w = pk2(lo_f(q.w) * rs, hi_f(q.w) * rs);
;                 *(LAS v4u*)(Kl + kr * 272 + qt * 64 + 16 * i) = o; *(LAS v4u*)(Vl + kr * 320 + qt * 64 + 16 * i) = vreg[i]; }
	v_mul_f32_e32 v16, v20, v16
	v_mul_f32_e32 v20, v82, v65
	v_mul_f32_e32 v17, v20, v17
	v_mul_f32_e32 v20, v82, v67
	v_mul_f32_e32 v18, v20, v18
	v_mul_f32_e32 v20, v82, v69
	v_mul_f32_e32 v19, v20, v19
	v_cvt_pk_bf16_f32 v142, v12, v13
	v_cvt_pk_bf16_f32 v143, v14, v15
	v_cvt_pk_bf16_f32 v144, v16, v17
	v_cvt_pk_bf16_f32 v145, v18, v19
	ds_read_b128 v[12:15], v39 offset:256
	ds_read_b128 v[16:19], v39 offset:272
	v_mul_f32_e32 v20, v82, v22
	s_waitcnt lgkmcnt(1)
	v_mul_f32_e32 v12, v20, v12
	v_mul_f32_e32 v20, v82, v70
	v_mul_f32_e32 v13, v20, v13
	v_mul_f32_e32 v20, v82, v72
	v_mul_f32_e32 v14, v20, v14
	v_mul_f32_e32 v20, v82, v24
	v_mul_f32_e32 v15, v20, v15
	v_mul_f32_e32 v20, v82, v28
	s_waitcnt lgkmcnt(0)
	v_mul_f32_e32 v16, v20, v16
	v_mul_f32_e32 v20, v82, v74
	v_mul_f32_e32 v17, v20, v17
	v_mul_f32_e32 v20, v82, v76
	v_mul_f32_e32 v18, v20, v18
	v_mul_f32_e32 v20, v82, v26
	v_mul_f32_e32 v19, v20, v19
	v_cvt_pk_bf16_f32 v146, v12, v13
	v_cvt_pk_bf16_f32 v147, v14, v15
	v_cvt_pk_bf16_f32 v148, v16, v17
	v_cvt_pk_bf16_f32 v149, v18, v19
	ds_read_b128 v[12:15], v39 offset:320
	ds_read_b128 v[16:19], v39 offset:336
	v_mul_f32_e32 v20, v82, v23
	s_waitcnt lgkmcnt(1)
	v_mul_f32_e32 v12, v20, v12
	v_mul_f32_e32 v20, v82, v71
	v_mul_f32_e32 v13, v20, v13
	v_mul_f32_e32 v20, v82, v73
	v_mul_f32_e32 v14, v20, v14
	v_mul_f32_e32 v20, v82, v25
	v_mul_f32_e32 v15, v20, v15
	v_mul_f32_e32 v20, v82, v29
	s_waitcnt lgkmcnt(0)
	v_mul_f32_e32 v16, v20, v16
	v_mul_f32_e32 v20, v82, v75
	v_mul_f32_e32 v17, v20, v17
	v_mul_f32_e32 v20, v82, v77
	v_mul_f32_e32 v18, v20, v18
	v_mul_f32_e32 v20, v82, v27
	v_mul_f32_e32 v19, v20, v19
	v_cvt_pk_bf16_f32 v150, v12, v13
	v_cvt_pk_bf16_f32 v151, v14, v15
	v_cvt_pk_bf16_f32 v152, v16, v17
	v_cvt_pk_bf16_f32 v153, v18, v19
	ds_read_b128 v[12:15], v39 offset:384
	ds_read_b128 v[16:19], v39 offset:400
	s_waitcnt lgkmcnt(1)
	v_mul_f32_e32 v4, v4, v12
	v_mul_f32_e32 v6, v6, v13
	v_mul_f32_e32 v12, v82, v30
	v_mul_f32_e32 v13, v82, v32
	v_mul_f32_e32 v12, v12, v14
	v_mul_f32_e32 v13, v13, v15
	v_mul_f32_e32 v14, v82, v36
	v_mul_f32_e32 v15, v82, v78
	s_waitcnt lgkmcnt(0)
	v_mul_f32_e32 v14, v14, v16
	v_mul_f32_e32 v15, v15, v17
	v_mul_f32_e32 v16, v82, v80
	v_mul_f32_e32 v17, v82, v34
	v_mul_f32_e32 v16, v16, v18
	v_mul_f32_e32 v17, v17, v19
	v_cvt_pk_bf16_f32 v154, v4, v6
	v_cvt_pk_bf16_f32 v155, v12, v13
	v_cvt_pk_bf16_f32 v156, v14, v15
	v_cvt_pk_bf16_f32 v157, v16, v17
	ds_read_b128 v[12:15], v39 offset:448
	ds_read_b128 v[16:19], v39 offset:464
	v_and_b32_e32 v4, 16, v8
	v_lshrrev_b32_e32 v6, 2, v8
	v_and_or_b32 v2, v2, 12, v4
	s_waitcnt lgkmcnt(1)
	v_mul_f32_e32 v5, v5, v12
	v_mul_f32_e32 v7, v7, v13
	v_cvt_pk_bf16_f32 v158, v5, v7
	v_xor_b32_e32 v5, 1, v194
	v_cmp_lt_i32_e32 vcc, v5, v38
	v_mul_f32_e32 v12, v82, v31
	v_mul_f32_e32 v13, v82, v33
	v_cndmask_b32_e32 v5, v194, v5, vcc
	v_lshlrev_b32_e32 v186, 2, v5
	v_xor_b32_e32 v5, 2, v194
	v_cmp_lt_i32_e32 vcc, v5, v38
	v_lshlrev_b32_e32 v22, 1, v2
	v_and_or_b32 v2, v6, 3, v185
	v_cndmask_b32_e32 v5, v194, v5, vcc
	v_lshlrev_b32_e32 v187, 2, v5
	v_mov_b32_e32 v5, s26
	v_mul_f32_e32 v12, v12, v14
	v_mul_f32_e32 v13, v13, v15
	v_mul_f32_e32 v14, v82, v37
	v_mul_f32_e32 v15, v82, v79
	v_mad_u32_u24 v23, v2, s15, v5
	v_add_u32_e32 v2, s7, v10
	s_waitcnt lgkmcnt(0)
	v_mul_f32_e32 v14, v14, v16
	v_mul_f32_e32 v15, v15, v17
	v_mul_f32_e32 v16, v82, v81
	v_mul_f32_e32 v17, v82, v35
	v_subrev_u32_e32 v199, 64, v2
	v_lshl_add_u32 v2, v11, 2, s25
	v_mul_f32_e32 v16, v16, v18
	v_mul_f32_e32 v17, v17, v19
	v_sub_u32_e32 v2, v2, v0
	v_cvt_pk_bf16_f32 v159, v12, v13
	v_cvt_pk_bf16_f32 v160, v14, v15
	v_cvt_pk_bf16_f32 v161, v16, v17
	v_mad_u32_u24 v18, v10, s16, v5
	v_lshlrev_b32_e32 v19, 4, v9
	v_mad_u32_u24 v20, v10, s15, v5
	v_mad_u32_u24 v21, v11, s16, v5
	v_subrev_u32_e32 v2, s13, v2
	v_readlane_b32 s13, v254, 3
	v_mov_b32_e32 v16, v1
	v_mov_b32_e32 v17, v1
	v_add_u32_e32 v200, s13, v2
	v_mov_b32_e32 v2, v1
	v_mov_b32_e32 v4, v1
	v_mov_b32_e32 v5, v1
	v_mov_b32_e32 v6, v1
	v_mov_b32_e32 v7, v1
	v_mov_b32_e32 v8, v1
	v_mov_b32_e32 v9, v1
	v_mov_b32_e32 v10, v1
	v_mov_b32_e32 v11, v1
	v_mov_b32_e32 v12, v1
	v_mov_b32_e32 v13, v1
	v_mov_b32_e32 v14, v1
	v_mov_b32_e32 v15, v1
	v_add_u32_e32 v201, v18, v19
	v_add_u32_e32 v202, v20, v19
	v_add_u32_e32 v203, v21, v0
	v_add_u32_e32 v204, v23, v22
	v_mov_b64_e32 v[32:33], v[16:17]
	v_mov_b64_e32 v[48:49], v[16:17]
	v_mov_b64_e32 v[64:65], v[16:17]
	s_sub_i32 s13, s14, s23
	s_movk_i32 s14, 0xc0
	v_mov_b64_e32 v[30:31], v[14:15]
	v_mov_b64_e32 v[28:29], v[12:13]
	v_mov_b64_e32 v[26:27], v[10:11]
	v_mov_b64_e32 v[24:25], v[8:9]
	v_mov_b64_e32 v[22:23], v[6:7]
	v_mov_b64_e32 v[20:21], v[4:5]
	v_mov_b64_e32 v[18:19], v[2:3]
	v_mov_b64_e32 v[46:47], v[14:15]
	v_mov_b64_e32 v[44:45], v[12:13]
	v_mov_b64_e32 v[42:43], v[10:11]
	v_mov_b64_e32 v[40:41], v[8:9]
	v_mov_b64_e32 v[38:39], v[6:7]
	v_mov_b64_e32 v[36:37], v[4:5]
	v_mov_b64_e32 v[34:35], v[2:3]
	v_mov_b64_e32 v[62:63], v[14:15]
	v_mov_b64_e32 v[60:61], v[12:13]
	v_mov_b64_e32 v[58:59], v[10:11]
	v_mov_b64_e32 v[56:57], v[8:9]
	v_mov_b64_e32 v[54:55], v[6:7]
	v_mov_b64_e32 v[52:53], v[4:5]
	v_mov_b64_e32 v[50:51], v[2:3]
; #define LAS __attribute__((address_space(3)))
; DI float lo_f(unsigned u) { return __uint_as_float(u << 16); }
; DI float hi_f(unsigned u) { return __uint_as_float(u & 0xffff0000u); }
; DI unsigned pk2(float lo, float hi) { return pg8::cvt_pk_bf16(lo, hi); }
; #define AT_LOAD(t_) do { const int ks0_ = 128 * (qb - 1) + 64 * (t_); if (ks0_ >= 0) { const size_t ktok_ = rowb + (size_t)(ks0_ + kr) * dil + r; const bf16* kp_ = P + pidx(ktok_, 1536 + head * 128 + qt * 32); \
;         _Pragma("unroll") for (int i = 0; i < 4; ++i) { kreg[i] = *(const v4u*)(kp_ + 8 * i); vreg[i] = *(const v4u*)(kp_ + (size_t)6 * TH * 256 + 8 * i); } } } while (0)
; DI void attn_unit(LAS unsigned char* lds, const bf16* P, bf16* OG, float* LSE, const float* relb, int u) {
;     ...
;     for (int t = tstart; t < 4; ++t) {
;         const int ks0 = 128 * (qb - 1) + 64 * t; const bool tvalid = ks0 >= 0;
;         __syncthreads();
;         if (tvalid) {
;             float ss = 0.f;
; #pragma unroll
;             for (int i = 0; i < 4; ++i) { const v4u q = kreg[i];
;                 ss += lo_f(q.x) * lo_f(q.x) + hi_f(q.x) * hi_f(q.x) + lo_f(q.y) * lo_f(q.y) + hi_f(q.y) * hi_f(q.y) + lo_f(q.z) * lo_f(q.z) + hi_f(q.z) * hi_f(q.z) + lo_f(q.w) * lo_f(q.w) + hi_f(q.w) * hi_f(q.w); }
;             ss += __shfl_xor(ss, 1); ss += __shfl_xor(ss, 2);
;             const float rs = rsqrtf(ss * (1.0f / 128.0f) + 1e-6f);
; #pragma unroll
;             for (int i = 0; i < 4; ++i) { const v4u q = kreg[i];
;                 v4u o; o.x = pk2(lo_f(q.x) * rs, hi_f(q.x) * rs); o.y = pk2(lo_f(q.y) * rs, hi_f(q.y) * rs); o.z = pk2(lo_f(q.z) * rs, hi_f(q.z) * rs); o.w = pk2(lo_f(q.w) * rs, hi_f(q.w) * rs);
;                 *(LAS v4u*)(Kl + kr * 272 + qt * 64 + 16 * i) = o; *(LAS v4u*)(Vl + kr * 320 + qt * 64 + 16 * i) = vreg[i]; }
;         }
;         __syncthreads();
;         if (t < 3) AT_LOAD(t + 1);
.LBB0_422:
	s_add_i32 s16, s23, s7
	s_add_i32 s15, s16, 0xffffff80
	s_cmp_lt_i32 s15, 0
	s_barrier
	s_cbranch_scc1 .LBB0_424
	s_waitcnt vmcnt(5)
	v_and_b32_e32 v73, 0xffff0000, v106
	s_waitcnt vmcnt(4)
	v_and_b32_e32 v72, 0xffff0000, v110
	v_lshlrev_b32_e32 v71, 16, v106
	v_lshlrev_b32_e32 v70, 16, v110
	v_pk_mul_f32 v[66:67], v[72:73], v[72:73]
	v_and_b32_e32 v89, 0xffff0000, v98
	v_and_b32_e32 v88, 0xffff0000, v102
	v_pk_fma_f32 v[66:67], v[70:71], v[70:71], v[66:67]
	v_lshlrev_b32_e32 v75, 16, v107
	v_lshlrev_b32_e32 v74, 16, v111
	v_lshlrev_b32_e32 v87, 16, v98
	v_lshlrev_b32_e32 v86, 16, v102
	v_pk_mul_f32 v[68:69], v[88:89], v[88:89]
	v_pk_fma_f32 v[66:67], v[74:75], v[74:75], v[66:67]
	v_and_b32_e32 v77, 0xffff0000, v107
	v_and_b32_e32 v76, 0xffff0000, v111
	v_pk_fma_f32 v[68:69], v[86:87], v[86:87], v[68:69]
	v_lshlrev_b32_e32 v91, 16, v99
	v_lshlrev_b32_e32 v90, 16, v103
	v_pk_fma_f32 v[66:67], v[76:77], v[76:77], v[66:67]
	v_lshlrev_b32_e32 v79, 16, v108
	v_lshlrev_b32_e32 v78, 16, v112
	v_pk_fma_f32 v[68:69], v[90:91], v[90:91], v[68:69]
	v_and_b32_e32 v93, 0xffff0000, v99
	v_and_b32_e32 v92, 0xffff0000, v103
	v_pk_fma_f32 v[66:67], v[78:79], v[78:79], v[66:67]
	v_and_b32_e32 v81, 0xffff0000, v108
	v_and_b32_e32 v80, 0xffff0000, v112
	v_pk_fma_f32 v[68:69], v[92:93], v[92:93], v[68:69]
	v_lshlrev_b32_e32 v95, 16, v100
	v_lshlrev_b32_e32 v94, 16, v104
	v_pk_fma_f32 v[66:67], v[80:81], v[80:81], v[66:67]
	v_lshlrev_b32_e32 v83, 16, v109
	v_lshlrev_b32_e32 v82, 16, v113
	v_pk_fma_f32 v[68:69], v[94:95], v[94:95], v[68:69]
	v_and_b32_e32 v97, 0xffff0000, v100
	v_and_b32_e32 v96, 0xffff0000, v104
	v_pk_fma_f32 v[66:67], v[82:83], v[82:83], v[66:67]
	v_and_b32_e32 v85, 0xffff0000, v109
	v_and_b32_e32 v84, 0xffff0000, v113
	v_pk_fma_f32 v[68:69], v[96:97], v[96:97], v[68:69]
	v_lshlrev_b32_e32 v163, 16, v101
	v_lshlrev_b32_e32 v162, 16, v105
	v_pk_fma_f32 v[66:67], v[84:85], v[84:85], v[66:67]
	v_pk_fma_f32 v[68:69], v[162:163], v[162:163], v[68:69]
	v_and_b32_e32 v165, 0xffff0000, v101
	v_and_b32_e32 v164, 0xffff0000, v105
	v_pk_fma_f32 v[68:69], v[164:165], v[164:165], v[68:69]
	v_add_f32_e32 v0, v66, v67
	v_add_f32_e32 v0, v0, v68
	v_add_f32_e32 v0, v0, v69
	ds_bpermute_b32 v66, v186, v0
	s_mov_b32 s17, 0x800000
	s_waitcnt lgkmcnt(0)
	v_add_f32_e32 v0, v0, v66
	ds_bpermute_b32 v66, v187, v0
	s_waitcnt lgkmcnt(0)
	v_add_f32_e32 v0, v0, v66
	v_fmamk_f32 v0, v0, 0x3c000000, v192
	v_mul_f32_e32 v66, 0x4b800000, v0
	v_cmp_gt_f32_e32 vcc, s17, v0
	s_nop 1
	v_cndmask_b32_e32 v0, v0, v66, vcc
	v_rsq_f32_e32 v0, v0
	s_nop 0
	v_mul_f32_e32 v66, 0x45800000, v0
	v_cndmask_b32_e32 v0, v0, v66, vcc
	v_mul_f32_e32 v66, v0, v70
	v_mul_f32_e32 v67, v0, v72
	v_cvt_pk_bf16_f32 v66, v66, v67
	v_mul_f32_e32 v67, v0, v74
	v_mul_f32_e32 v68, v0, v76
	v_cvt_pk_bf16_f32 v67, v67, v68
	v_mul_f32_e32 v68, v0, v78
	v_mul_f32_e32 v69, v0, v80
	v_cvt_pk_bf16_f32 v68, v68, v69
	v_mul_f32_e32 v69, v0, v82
	v_mul_f32_e32 v70, v0, v84
	v_cvt_pk_bf16_f32 v69, v69, v70
	ds_write_b128 v201, v[66:69]
	s_waitcnt vmcnt(3)
	ds_write_b128 v202, v[114:117] offset:17408
	v_mul_f32_e32 v66, v0, v71
	v_mul_f32_e32 v67, v0, v73
	v_cvt_pk_bf16_f32 v66, v66, v67
	v_mul_f32_e32 v67, v0, v75
	v_mul_f32_e32 v68, v0, v77
	v_cvt_pk_bf16_f32 v67, v67, v68
	v_mul_f32_e32 v68, v0, v79
	v_mul_f32_e32 v69, v0, v81
	v_cvt_pk_bf16_f32 v68, v68, v69
	v_mul_f32_e32 v69, v0, v83
	v_mul_f32_e32 v70, v0, v85
	v_cvt_pk_bf16_f32 v69, v69, v70
	ds_write_b128 v201, v[66:69] offset:64
	s_waitcnt vmcnt(0)
	ds_write_b128 v202, v[126:129] offset:17472
	v_mul_f32_e32 v66, v0, v86
	v_mul_f32_e32 v67, v0, v88
	v_cvt_pk_bf16_f32 v66, v66, v67
	v_mul_f32_e32 v67, v0, v90
	v_mul_f32_e32 v68, v0, v92
	v_cvt_pk_bf16_f32 v67, v67, v68
	v_mul_f32_e32 v68, v0, v94
	v_mul_f32_e32 v69, v0, v96
	v_cvt_pk_bf16_f32 v68, v68, v69
	v_mul_f32_e32 v69, v0, v162
	v_mul_f32_e32 v70, v0, v164
	v_cvt_pk_bf16_f32 v69, v69, v70
	ds_write_b128 v201, v[66:69] offset:128
	ds_write_b128 v202, v[122:125] offset:17536
	v_mul_f32_e32 v66, v0, v87
	v_mul_f32_e32 v67, v0, v89
	v_cvt_pk_bf16_f32 v66, v66, v67
	v_mul_f32_e32 v67, v0, v91
	v_mul_f32_e32 v68, v0, v93
	v_cvt_pk_bf16_f32 v67, v67, v68
	v_mul_f32_e32 v68, v0, v95
	v_mul_f32_e32 v69, v0, v97
	v_cvt_pk_bf16_f32 v68, v68, v69
	v_mul_f32_e32 v69, v0, v163
	v_mul_f32_e32 v0, v0, v165
	v_cvt_pk_bf16_f32 v69, v69, v0
	ds_write_b128 v201, v[66:69] offset:192
	ds_write_b128 v202, v[118:121] offset:17600
.LBB0_424:
	s_cmp_eq_u32 s23, s14
	s_waitcnt lgkmcnt(0)
	s_barrier
	s_cbranch_scc1 .LBB0_427
	s_sub_i32 s16, s16, 64
	s_cmp_lt_i32 s16, 0
	s_cbranch_scc1 .LBB0_427
	v_add_u32_e32 v0, s23, v199
	v_lshlrev_b64 v[66:67], s8, v[0:1]
	v_lshl_add_u64 v[66:67], v[66:67], 0, s[10:11]
	v_lshlrev_b64 v[66:67], 9, v[66:67]
	v_lshl_add_u64 v[66:67], v[180:181], 0, v[66:67]
	s_mov_b64 s[16:17], 0x6000000
	v_lshl_add_u64 v[68:69], v[66:67], 0, s[16:17]
	s_mov_b32 s16, 0x6000000
	global_load_dwordx4 v[98:101], v[66:67], off offset:192
	global_load_dwordx4 v[102:105], v[66:67], off offset:128
	global_load_dwordx4 v[106:109], v[66:67], off offset:64
	global_load_dwordx4 v[110:113], v[66:67], off
	v_add_co_u32_e32 v66, vcc, s16, v66
	s_nop 1
	v_addc_co_u32_e32 v67, vcc, 0, v67, vcc
	global_load_dwordx4 v[114:117], v[66:67], off
	global_load_dwordx4 v[118:121], v[68:69], off offset:192
	global_load_dwordx4 v[122:125], v[68:69], off offset:128
	global_load_dwordx4 v[126:129], v[68:69], off offset:64
